# attention loops: K/V fragment ds_reads issued two MFMAs ahead (second buffer v252-255, counted lgkmcnt(1)), K addresses hoisted; stagger sleeps removed (no longer help)
# speedup vs baseline: 1.0380x; 1.0122x over previous
.LBB0_226:
	s_lshl_b32 s86, s33, 15
	v_or_b32_e32 v102, s86, v200
	s_waitcnt lgkmcnt(0)
	s_barrier
	v_add_u32_e32 v129, v102, v202
	v_add_u32_e32 v151, v102, v203
	v_add_u32_e32 v157, v102, v204
	v_add_u32_e32 v161, v102, v205
	ds_read_b128 v[98:101], v129
	ds_read_b128 v[252:255], v151
	v_add_f32_e32 v232, s74, v162
	v_add_f32_e32 v233, s75, v162
	v_add_f32_e32 v234, s64, v162
	v_add_f32_e32 v235, s65, v162
	v_add_f32_e32 v236, s58, v162
	v_add_f32_e32 v237, s59, v162
	v_add_f32_e32 v238, s56, v162
	v_add_f32_e32 v239, s57, v162
	s_waitcnt vmcnt(3) lgkmcnt(1)
	v_mfma_f32_32x32x16_bf16 v[216:231], v[98:101], v[82:85], v[216:231]
	ds_read_b128 v[98:101], v157
	s_add_i32 s6, s33, 1
	v_add_u32_e32 v128, 1, v128
	s_cmp_lg_u32 s33, 2
	v_cmp_ge_i32_e32 vcc, v128, v155
	v_add_f32_e32 v240, s54, v162
	v_add_f32_e32 v241, s55, v162
	v_add_f32_e32 v242, s48, v162
	v_add_f32_e32 v243, s49, v162
	s_waitcnt vmcnt(2) lgkmcnt(1)
	v_mfma_f32_32x32x16_bf16 v[216:231], v[252:255], v[86:89], v[216:231]
	ds_read_b128 v[252:255], v161
	s_cselect_b32 s33, s6, 0
	v_add_u32_e32 v127, 64, v127
	s_or_b64 s[84:85], vcc, s[84:85]
	v_add_f32_e32 v244, s34, v162
	v_add_f32_e32 v245, s35, v162
	v_add_f32_e32 v246, s30, v162
	v_add_f32_e32 v247, s31, v162
	v_fma_f32 v232, v106, |v232|, v146
	v_fma_f32 v233, v106, |v233|, v146
	s_waitcnt vmcnt(1) lgkmcnt(1)
	v_mfma_f32_32x32x16_bf16 v[216:231], v[98:101], v[90:93], v[216:231]
	ds_read_b128 v[162:165], v129 offset:8192
	v_fma_f32 v234, v106, |v234|, v146
	v_fma_f32 v235, v106, |v235|, v146
	v_fma_f32 v236, v106, |v236|, v146
	v_fma_f32 v237, v106, |v237|, v146
	v_fma_f32 v238, v106, |v238|, v146
	v_fma_f32 v239, v106, |v239|, v146
	s_waitcnt vmcnt(0) lgkmcnt(1)
	v_mfma_f32_32x32x16_bf16 v[216:231], v[252:255], v[94:97], v[216:231]
	ds_read_b128 v[252:255], v151 offset:8192
	v_fma_f32 v240, v106, |v240|, v146
	v_fma_f32 v241, v106, |v241|, v146
	v_fma_f32 v242, v106, |v242|, v146
	v_fma_f32 v243, v106, |v243|, v146
	v_fma_f32 v244, v106, |v244|, v146
	v_fma_f32 v245, v106, |v245|, v146
	v_fma_f32 v246, v106, |v246|, v146
	v_fma_f32 v247, v106, |v247|, v146
	s_nop 2
	v_exp_f32_e32 v66, v216
	v_exp_f32_e32 v166, v217
	v_exp_f32_e32 v168, v218
	v_exp_f32_e32 v170, v219
	v_add_f32_e32 v132, 0, v66
	s_waitcnt lgkmcnt(1)
	v_mfma_f32_32x32x16_bf16 v[232:247], v[162:165], v[82:85], v[232:247]
	ds_read_b128 v[162:165], v157 offset:8192
	v_exp_f32_e32 v188, v228
	v_exp_f32_e32 v212, v229
	v_exp_f32_e32 v214, v230
	v_exp_f32_e32 v250, v231
	v_cvt_pk_bf16_f32 v98, v66, v166
	s_waitcnt lgkmcnt(1)
	v_mfma_f32_32x32x16_bf16 v[232:247], v[252:255], v[86:89], v[232:247]
	ds_read_b128 v[252:255], v161 offset:8192
	v_exp_f32_e32 v172, v220
	v_exp_f32_e32 v174, v221
	v_exp_f32_e32 v176, v222
	v_exp_f32_e32 v178, v223
	s_waitcnt lgkmcnt(1)
	v_mfma_f32_32x32x16_bf16 v[232:247], v[162:165], v[90:93], v[232:247]
	v_exp_f32_e32 v180, v224
	v_exp_f32_e32 v182, v225
	v_exp_f32_e32 v184, v226
	v_exp_f32_e32 v186, v227
	s_waitcnt lgkmcnt(0)
	s_barrier
	s_waitcnt lgkmcnt(0)
	v_mfma_f32_32x32x16_bf16 v[232:247], v[252:255], v[94:97], v[232:247]
	v_cvt_pk_bf16_f32 v99, v168, v170
	v_cvt_pk_bf16_f32 v100, v172, v174
	v_cvt_pk_bf16_f32 v101, v176, v178
	v_cvt_pk_bf16_f32 v102, v180, v182
	v_cvt_pk_bf16_f32 v103, v184, v186
	v_cvt_pk_bf16_f32 v104, v188, v212
	v_cvt_pk_bf16_f32 v105, v214, v250
	v_or_b32_e32 v80, s86, v193
	v_add_u32_e32 v81, v80, v195
	ds_read_b128 v[74:77], v81 offset:16384
	v_add_u32_e32 v129, v80, v196
	s_nop 0
	v_exp_f32_e32 v251, v246
	v_exp_f32_e32 v161, v247
	v_exp_f32_e32 v183, v240
	v_exp_f32_e32 v185, v241
	v_exp_f32_e32 v187, v242
	v_exp_f32_e32 v189, v243
	ds_read_b128 v[252:255], v129 offset:16384
	s_waitcnt lgkmcnt(1)
	v_mfma_f32_32x32x16_bf16 v[50:65], v[74:77], v[98:101], v[50:65]
	ds_read_b128 v[74:77], v81 offset:20480
	v_exp_f32_e32 v167, v232
	v_exp_f32_e32 v169, v233
	v_exp_f32_e32 v171, v234
	v_exp_f32_e32 v173, v235
	v_pk_add_f32 v[66:67], v[166:167], v[132:133]
	v_exp_f32_e32 v175, v236
	s_waitcnt lgkmcnt(1)
	v_mfma_f32_32x32x16_bf16 v[50:65], v[252:255], v[102:105], v[50:65]
	ds_read_b128 v[252:255], v129 offset:20480
	v_add_f32_e64 v66, v168, v66
	v_add_f32_e64 v67, v169, v67
	v_exp_f32_e32 v177, v237
	v_pk_add_f32 v[66:67], v[170:171], v[66:67]
	v_exp_f32_e32 v179, v238
	v_pk_add_f32 v[66:67], v[172:173], v[66:67]
	v_exp_f32_e32 v181, v239
	s_waitcnt lgkmcnt(1)
	v_mfma_f32_32x32x16_bf16 v[34:49], v[74:77], v[98:101], v[34:49]
	ds_read_b128 v[74:77], v81 offset:24576
	v_add_f32_e64 v66, v174, v66
	v_add_f32_e64 v67, v175, v67
	v_exp_f32_e32 v213, v244
	v_pk_add_f32 v[66:67], v[176:177], v[66:67]
	v_exp_f32_e32 v215, v245
	v_pk_add_f32 v[66:67], v[178:179], v[66:67]
	v_cvt_pk_bf16_f32 v68, v175, v177
	s_waitcnt lgkmcnt(1)
	v_mfma_f32_32x32x16_bf16 v[34:49], v[252:255], v[102:105], v[34:49]
	ds_read_b128 v[252:255], v129 offset:24576
	v_add_f32_e64 v66, v180, v66
	v_add_f32_e64 v67, v181, v67
	v_cvt_pk_bf16_f32 v69, v179, v181
	v_add_f32_e64 v66, v182, v66
	v_add_f32_e64 v67, v183, v67
	v_cvt_pk_bf16_f32 v70, v183, v185
	v_pk_add_f32 v[66:67], v[184:185], v[66:67]
	v_cvt_pk_bf16_f32 v71, v187, v189
	s_waitcnt lgkmcnt(1)
	v_mfma_f32_32x32x16_bf16 v[18:33], v[74:77], v[98:101], v[18:33]
	ds_read_b128 v[74:77], v81 offset:28672
	v_add_f32_e64 v66, v186, v66
	v_add_f32_e64 v67, v187, v67
	v_cvt_pk_bf16_f32 v72, v213, v215
	v_add_f32_e64 v66, v188, v66
	v_add_f32_e64 v67, v189, v67
	v_cvt_pk_bf16_f32 v73, v251, v161
	v_pk_add_f32 v[66:67], v[212:213], v[66:67]
	s_waitcnt lgkmcnt(1)
	v_mfma_f32_32x32x16_bf16 v[18:33], v[252:255], v[102:105], v[18:33]
	ds_read_b128 v[252:255], v129 offset:28672
	v_add_u32_e32 v81, v80, v197
	v_add_f32_e64 v66, v214, v66
	v_add_f32_e64 v67, v215, v67
	v_add_u32_e32 v80, v80, v198
	v_pk_add_f32 v[66:67], v[250:251], v[66:67]
	s_nop 0
	v_pk_add_f32 v[78:79], v[160:161], v[66:67]
	s_waitcnt lgkmcnt(1)
	v_mfma_f32_32x32x16_bf16 v[2:17], v[74:77], v[98:101], v[2:17]
	ds_read_b128 v[74:77], v81 offset:16384
	v_cvt_pk_bf16_f32 v66, v167, v169
	v_cvt_pk_bf16_f32 v67, v171, v173
	v_add_f32_e32 v160, v78, v79
	s_waitcnt lgkmcnt(1)
	v_mfma_f32_32x32x16_bf16 v[2:17], v[252:255], v[102:105], v[2:17]
	ds_read_b128 v[252:255], v80 offset:16384
	v_cvt_f32_i32_e32 v162, v127
	v_add_f32_e32 v217, 1.0, v162
	v_add_f32_e32 v218, s12, v162
	v_add_f32_e32 v219, s13, v162
	s_waitcnt lgkmcnt(1)
	v_mfma_f32_32x32x16_bf16 v[50:65], v[74:77], v[66:69], v[50:65]
	ds_read_b128 v[74:77], v81 offset:20480
	v_add_f32_e32 v220, s16, v162
	v_add_f32_e32 v221, s17, v162
	v_add_f32_e32 v222, s18, v162
	v_add_f32_e32 v223, s19, v162
	s_waitcnt lgkmcnt(1)
	v_mfma_f32_32x32x16_bf16 v[50:65], v[252:255], v[70:73], v[50:65]
	ds_read_b128 v[252:255], v80 offset:20480
	v_add_f32_e32 v224, s20, v162
	v_add_f32_e32 v225, s21, v162
	v_add_f32_e32 v226, s22, v162
	v_add_f32_e32 v227, s23, v162
	s_waitcnt lgkmcnt(1)
	v_mfma_f32_32x32x16_bf16 v[34:49], v[74:77], v[66:69], v[34:49]
	ds_read_b128 v[74:77], v81 offset:24576
	v_add_f32_e32 v228, s26, v162
	v_add_f32_e32 v229, s27, v162
	v_add_f32_e32 v230, s28, v162
	v_add_f32_e32 v231, s29, v162
	s_waitcnt lgkmcnt(1)
	v_mfma_f32_32x32x16_bf16 v[34:49], v[252:255], v[70:73], v[34:49]
	ds_read_b128 v[252:255], v80 offset:24576
	v_fma_f32 v216, v106, |v162|, v146
	v_fma_f32 v217, v106, |v217|, v146
	v_fma_f32 v218, v106, |v218|, v146
	v_fma_f32 v219, v106, |v219|, v146
	s_waitcnt lgkmcnt(1)
	v_mfma_f32_32x32x16_bf16 v[18:33], v[74:77], v[66:69], v[18:33]
	ds_read_b128 v[74:77], v81 offset:28672
	v_fma_f32 v220, v106, |v220|, v146
	v_fma_f32 v221, v106, |v221|, v146
	v_fma_f32 v222, v106, |v222|, v146
	v_fma_f32 v223, v106, |v223|, v146
	s_waitcnt lgkmcnt(1)
	v_mfma_f32_32x32x16_bf16 v[18:33], v[252:255], v[70:73], v[18:33]
	ds_read_b128 v[252:255], v80 offset:28672
	v_fma_f32 v224, v106, |v224|, v146
	v_fma_f32 v225, v106, |v225|, v146
	v_fma_f32 v226, v106, |v226|, v146
	v_fma_f32 v227, v106, |v227|, v146
	s_waitcnt lgkmcnt(1)
	v_mfma_f32_32x32x16_bf16 v[2:17], v[74:77], v[66:69], v[2:17]
	v_fma_f32 v228, v106, |v228|, v146
	v_fma_f32 v229, v106, |v229|, v146
	v_fma_f32 v230, v106, |v230|, v146
	v_fma_f32 v231, v106, |v231|, v146
	s_waitcnt lgkmcnt(0)
	v_mfma_f32_32x32x16_bf16 v[2:17], v[252:255], v[70:73], v[2:17]
	s_andn2_b64 exec, exec, s[84:85]
	s_cbranch_execnz .LBB0_226
	s_or_b64 exec, exec, s[84:85]

.LBB0_232:
	s_or_b64 exec, exec, s[86:87]
	s_and_b64 s[6:7], exec, vcc
	s_or_b64 s[84:85], s[6:7], s[84:85]
	s_lshl_b32 s86, s90, 15
	v_or_b32_e32 v102, s86, v200
	v_add_u32_e32 v127, v102, v202
	v_add_u32_e32 v129, v102, v203
	v_add_u32_e32 v157, v102, v204
	v_add_u32_e32 v161, v102, v205
	ds_read_b128 v[98:101], v127
	ds_read_b128 v[252:255], v129
	v_add_f32_e32 v232, s74, v212
	v_add_f32_e32 v233, s75, v212
	v_add_f32_e32 v234, s64, v212
	v_add_f32_e32 v235, s65, v212
	v_add_f32_e32 v236, s58, v212
	v_add_f32_e32 v237, s59, v212
	v_add_f32_e32 v238, s56, v212
	v_add_f32_e32 v239, s57, v212
	s_waitcnt lgkmcnt(1)
	v_mfma_f32_32x32x16_bf16 v[216:231], v[98:101], v[82:85], v[216:231]
	ds_read_b128 v[98:101], v157
	v_add_u32_e32 v141, 1, v141
	s_mov_b32 s90, s33
	v_add_f32_e32 v240, s54, v212
	v_add_f32_e32 v241, s55, v212
	v_add_f32_e32 v242, s48, v212
	v_add_f32_e32 v243, s49, v212
	s_waitcnt lgkmcnt(1)
	v_mfma_f32_32x32x16_bf16 v[216:231], v[252:255], v[86:89], v[216:231]
	ds_read_b128 v[252:255], v161
	v_add_f32_e32 v244, s34, v212
	v_add_f32_e32 v245, s35, v212
	v_add_f32_e32 v246, s30, v212
	v_add_f32_e32 v247, s31, v212
	v_fma_f32 v232, v110, |v232|, v146
	v_fma_f32 v233, v110, |v233|, v146
	s_waitcnt lgkmcnt(1)
	v_mfma_f32_32x32x16_bf16 v[216:231], v[98:101], v[90:93], v[216:231]
	ds_read_b128 v[212:215], v127 offset:8192
	v_fma_f32 v234, v110, |v234|, v146
	v_fma_f32 v235, v110, |v235|, v146
	v_fma_f32 v236, v110, |v236|, v146
	v_fma_f32 v237, v110, |v237|, v146
	v_fma_f32 v238, v110, |v238|, v146
	v_fma_f32 v239, v110, |v239|, v146
	s_waitcnt lgkmcnt(1)
	v_mfma_f32_32x32x16_bf16 v[216:231], v[252:255], v[94:97], v[216:231]
	ds_read_b128 v[252:255], v129 offset:8192
	v_fma_f32 v240, v110, |v240|, v146
	v_fma_f32 v241, v110, |v241|, v146
	v_fma_f32 v242, v110, |v242|, v146
	v_fma_f32 v243, v110, |v243|, v146
	v_fma_f32 v244, v110, |v244|, v146
	v_fma_f32 v245, v110, |v245|, v146
	v_fma_f32 v246, v110, |v246|, v146
	v_fma_f32 v247, v110, |v247|, v146
	s_nop 2
	v_exp_f32_e32 v66, v216
	v_exp_f32_e32 v128, v217
	v_exp_f32_e32 v164, v218
	v_exp_f32_e32 v162, v219
	v_add_f32_e32 v132, 0, v66
	s_waitcnt lgkmcnt(1)
	v_mfma_f32_32x32x16_bf16 v[232:247], v[212:215], v[82:85], v[232:247]
	ds_read_b128 v[212:215], v157 offset:8192
	v_exp_f32_e32 v184, v228
	v_exp_f32_e32 v182, v229
	v_exp_f32_e32 v188, v230
	v_exp_f32_e32 v186, v231
	v_cvt_pk_bf16_f32 v102, v66, v128
	s_waitcnt lgkmcnt(1)
	v_mfma_f32_32x32x16_bf16 v[232:247], v[252:255], v[86:89], v[232:247]
	ds_read_b128 v[252:255], v161 offset:8192
	v_exp_f32_e32 v168, v220
	v_exp_f32_e32 v166, v221
	v_exp_f32_e32 v172, v222
	v_exp_f32_e32 v170, v223
	s_waitcnt lgkmcnt(1)
	v_mfma_f32_32x32x16_bf16 v[232:247], v[212:215], v[90:93], v[232:247]
	v_exp_f32_e32 v176, v224
	v_exp_f32_e32 v174, v225
	v_exp_f32_e32 v180, v226
	v_exp_f32_e32 v178, v227
	s_waitcnt lgkmcnt(0)
	s_barrier
	s_waitcnt lgkmcnt(0)
	v_mfma_f32_32x32x16_bf16 v[232:247], v[252:255], v[94:97], v[232:247]
	v_cvt_pk_bf16_f32 v103, v164, v162
	v_cvt_pk_bf16_f32 v104, v168, v166
	v_cvt_pk_bf16_f32 v105, v172, v170
	v_cvt_pk_bf16_f32 v98, v176, v174
	v_cvt_pk_bf16_f32 v99, v180, v178
	v_cvt_pk_bf16_f32 v100, v184, v182
	v_cvt_pk_bf16_f32 v101, v188, v186
	v_or_b32_e32 v80, s86, v193
	v_add_u32_e32 v81, v80, v195
	ds_read_b128 v[76:79], v81 offset:16384
	v_add_u32_e32 v127, v80, v196
	s_nop 0
	v_exp_f32_e32 v187, v246
	v_exp_f32_e32 v161, v247
	v_exp_f32_e32 v179, v242
	v_exp_f32_e32 v185, v243
	v_exp_f32_e32 v183, v244
	v_exp_f32_e32 v189, v245
	ds_read_b128 v[252:255], v127 offset:16384
	s_waitcnt lgkmcnt(1)
	v_mfma_f32_32x32x16_bf16 v[50:65], v[76:79], v[102:105], v[50:65]
	ds_read_b128 v[76:79], v81 offset:20480
	v_exp_f32_e32 v129, v232
	v_exp_f32_e32 v165, v233
	v_exp_f32_e32 v163, v234
	v_exp_f32_e32 v169, v235
	v_pk_add_f32 v[66:67], v[128:129], v[132:133]
	v_exp_f32_e32 v167, v236
	s_waitcnt lgkmcnt(1)
	v_mfma_f32_32x32x16_bf16 v[50:65], v[252:255], v[98:101], v[50:65]
	ds_read_b128 v[252:255], v127 offset:20480
	v_add_f32_e64 v66, v164, v66
	v_add_f32_e64 v67, v165, v67
	v_exp_f32_e32 v173, v237
	v_pk_add_f32 v[66:67], v[162:163], v[66:67]
	v_exp_f32_e32 v171, v238
	v_exp_f32_e32 v177, v239
	v_pk_add_f32 v[66:67], v[168:169], v[66:67]
	s_waitcnt lgkmcnt(1)
	v_mfma_f32_32x32x16_bf16 v[34:49], v[76:79], v[102:105], v[34:49]
	ds_read_b128 v[76:79], v81 offset:24576
	v_exp_f32_e32 v175, v240
	v_pk_add_f32 v[66:67], v[166:167], v[66:67]
	v_exp_f32_e32 v181, v241
	v_pk_add_f32 v[66:67], v[172:173], v[66:67]
	v_cvt_pk_bf16_f32 v70, v129, v165
	v_pk_add_f32 v[66:67], v[170:171], v[66:67]
	s_waitcnt lgkmcnt(1)
	v_mfma_f32_32x32x16_bf16 v[34:49], v[252:255], v[98:101], v[34:49]
	ds_read_b128 v[252:255], v127 offset:24576
	v_cvt_pk_bf16_f32 v71, v163, v169
	v_cvt_pk_bf16_f32 v72, v167, v173
	v_cvt_pk_bf16_f32 v73, v171, v177
	v_add_f32_e64 v66, v176, v66
	v_add_f32_e64 v67, v177, v67
	v_cvt_pk_bf16_f32 v68, v183, v189
	v_pk_add_f32 v[66:67], v[174:175], v[66:67]
	s_waitcnt lgkmcnt(1)
	v_mfma_f32_32x32x16_bf16 v[18:33], v[76:79], v[102:105], v[18:33]
	ds_read_b128 v[76:79], v81 offset:28672
	v_add_f32_e64 v66, v180, v66
	v_add_f32_e64 v67, v181, v67
	v_cvt_pk_bf16_f32 v69, v187, v161
	v_add_f32_e64 v66, v178, v66
	v_add_f32_e64 v67, v179, v67
	v_pk_add_f32 v[66:67], v[184:185], v[66:67]
	s_waitcnt lgkmcnt(1)
	v_mfma_f32_32x32x16_bf16 v[18:33], v[252:255], v[98:101], v[18:33]
	ds_read_b128 v[252:255], v127 offset:28672
	v_add_u32_e32 v81, v80, v197
	v_add_u32_e32 v80, v80, v198
	v_add_f32_e64 v66, v182, v66
	v_add_f32_e64 v67, v183, v67
	v_pk_add_f32 v[66:67], v[188:189], v[66:67]
	s_waitcnt lgkmcnt(1)
	v_mfma_f32_32x32x16_bf16 v[2:17], v[76:79], v[102:105], v[2:17]
	ds_read_b128 v[76:79], v81 offset:16384
	v_add_f32_e64 v66, v186, v66
	v_add_f32_e64 v67, v187, v67
	v_add_f32_e64 v74, v160, v66
	v_add_f32_e64 v75, v161, v67
	v_cvt_pk_bf16_f32 v66, v175, v181
	v_cvt_pk_bf16_f32 v67, v179, v185
	v_add_f32_e32 v160, v74, v75
	s_waitcnt lgkmcnt(1)
	v_mfma_f32_32x32x16_bf16 v[2:17], v[252:255], v[98:101], v[2:17]
	ds_read_b128 v[252:255], v80 offset:16384
	v_add_u32_e32 v250, v151, v126
	v_cvt_f32_i32_e32 v212, v250
	v_add_f32_e32 v217, 1.0, v212
	v_add_f32_e32 v218, s12, v212
	v_add_f32_e32 v219, s13, v212
	s_waitcnt lgkmcnt(1)
	v_mfma_f32_32x32x16_bf16 v[50:65], v[76:79], v[70:73], v[50:65]
	ds_read_b128 v[76:79], v81 offset:20480
	v_add_f32_e32 v220, s16, v212
	v_add_f32_e32 v221, s17, v212
	v_add_f32_e32 v222, s18, v212
	v_add_f32_e32 v223, s19, v212
	s_waitcnt lgkmcnt(1)
	v_mfma_f32_32x32x16_bf16 v[50:65], v[252:255], v[66:69], v[50:65]
	ds_read_b128 v[252:255], v80 offset:20480
	v_add_f32_e32 v224, s20, v212
	v_add_f32_e32 v225, s21, v212
	v_add_f32_e32 v226, s22, v212
	v_add_f32_e32 v227, s23, v212
	s_waitcnt lgkmcnt(1)
	v_mfma_f32_32x32x16_bf16 v[34:49], v[76:79], v[70:73], v[34:49]
	ds_read_b128 v[76:79], v81 offset:24576
	v_add_f32_e32 v228, s26, v212
	v_add_f32_e32 v229, s27, v212
	v_add_f32_e32 v230, s28, v212
	v_add_f32_e32 v231, s29, v212
	s_waitcnt lgkmcnt(1)
	v_mfma_f32_32x32x16_bf16 v[34:49], v[252:255], v[66:69], v[34:49]
	ds_read_b128 v[252:255], v80 offset:24576
	v_fma_f32 v216, v110, |v212|, v146
	v_fma_f32 v217, v110, |v217|, v146
	v_fma_f32 v218, v110, |v218|, v146
	v_fma_f32 v219, v110, |v219|, v146
	s_waitcnt lgkmcnt(1)
	v_mfma_f32_32x32x16_bf16 v[18:33], v[76:79], v[70:73], v[18:33]
	ds_read_b128 v[76:79], v81 offset:28672
	v_fma_f32 v220, v110, |v220|, v146
	v_fma_f32 v221, v110, |v221|, v146
	v_fma_f32 v222, v110, |v222|, v146
	v_fma_f32 v223, v110, |v223|, v146
	s_waitcnt lgkmcnt(1)
	v_mfma_f32_32x32x16_bf16 v[18:33], v[252:255], v[66:69], v[18:33]
	ds_read_b128 v[252:255], v80 offset:28672
	v_fma_f32 v224, v110, |v224|, v146
	v_fma_f32 v225, v110, |v225|, v146
	v_fma_f32 v226, v110, |v226|, v146
	v_fma_f32 v227, v110, |v227|, v146
	s_waitcnt lgkmcnt(1)
	v_mfma_f32_32x32x16_bf16 v[2:17], v[76:79], v[70:73], v[2:17]
	v_fma_f32 v228, v110, |v228|, v146
	v_fma_f32 v229, v110, |v229|, v146
	v_fma_f32 v230, v110, |v230|, v146
	v_fma_f32 v231, v110, |v231|, v146
	s_waitcnt lgkmcnt(0)
	v_mfma_f32_32x32x16_bf16 v[2:17], v[252:255], v[66:69], v[2:17]
	v_mov_b32_e32 v66, v126
	s_andn2_b64 exec, exec, s[84:85]
	s_cbranch_execz .LBB0_237
